# LN trip: issue both rows' y+residual loads before the first wait (row-0 fp16 cvt ladder moved after row-1 loads, vmcnt 11..8)
# speedup vs baseline: 1.0056x; 1.0056x over previous
; DI float h_lo(unsigned u) { return (float)__builtin_bit_cast(h16v2, u)[0]; }
; DI float h_hi(unsigned u) { return (float)__builtin_bit_cast(h16v2, u)[1]; }
; DI void phase_ln(const Params& p, int layer, int gw, int NGW, int lane) {
;     ...
;         for (int q = 0; q < R; ++q) {
;             const u32x4* yb = (const u32x4*)(hb + (size_t)rr[q] * D) + lane;
;             u32x4 yv[4];
; #pragma unroll
;             for (int j = 0; j < 4; ++j) yv[j] = __builtin_nontemporal_load(yb + 64 * j);
;             if (layer == 0) {
;                 const f32x4* src32 = (const f32x4*)(rr[q] < SEQ ? p.x + (size_t)rr[q] * D : p.meta + (size_t)(rr[q] - SEQ) * D) + 2 * lane;
; #pragma unroll
;                 for (int j = 0; j < 4; ++j) { const f32x4 a0 = src32[128 * j], a1 = src32[128 * j + 1];
;                     v[q][8 * j + 0] = a0[0]; v[q][8 * j + 1] = a0[1]; v[q][8 * j + 2] = a0[2]; v[q][8 * j + 3] = a0[3];
;                     v[q][8 * j + 4] = a1[0]; v[q][8 * j + 5] = a1[1]; v[q][8 * j + 6] = a1[2]; v[q][8 * j + 7] = a1[3]; }
;             } else {
;                 const u32x4* src16 = (const u32x4*)(h16in + (size_t)rr[q] * D) + lane;
; #pragma unroll
;                 for (int j = 0; j < 4; ++j) { const u32x4 hh = __builtin_nontemporal_load(src16 + 64 * j);
;                     v[q][8 * j + 0] = h_lo(hh.x); v[q][8 * j + 1] = h_hi(hh.x); v[q][8 * j + 2] = h_lo(hh.y); v[q][8 * j + 3] = h_hi(hh.y);
;                     v[q][8 * j + 4] = h_lo(hh.z); v[q][8 * j + 5] = h_hi(hh.z); v[q][8 * j + 6] = h_lo(hh.w); v[q][8 * j + 7] = h_hi(hh.w); }
;             }
.LBB0_357:
	v_lshl_add_u64 v[132:133], s[50:51], 0, v[98:99]
	v_add_co_u32_e32 v2, vcc, 0x8400000, v132
	s_nop 1
	v_addc_co_u32_e32 v3, vcc, 0, v133, vcc
	global_load_dwordx4 v[30:33], v[2:3], off nt
	global_load_dwordx4 v[10:13], v[2:3], off offset:1024 nt
	global_load_dwordx4 v[6:9], v[2:3], off offset:2048 nt
	s_nop 0
	global_load_dwordx4 v[2:5], v[2:3], off offset:3072 nt
	s_and_b64 vcc, exec, s[40:41]
	s_cbranch_vccz .LBB0_399
	v_lshl_add_u64 v[26:27], s[46:47], 0, v[98:99]
	global_load_dwordx4 v[14:17], v[26:27], off nt
	global_load_dwordx4 v[18:21], v[26:27], off offset:1024 nt
	global_load_dwordx4 v[22:25], v[26:27], off offset:2048 nt
	s_nop 0
	global_load_dwordx4 v[228:231], v[26:27], off offset:3072 nt
	s_cbranch_execnz .LBB0_360

; DI float h_lo(unsigned u) { return (float)__builtin_bit_cast(h16v2, u)[0]; }
; DI float h_hi(unsigned u) { return (float)__builtin_bit_cast(h16v2, u)[1]; }
; DI void phase_ln(const Params& p, int layer, int gw, int NGW, int lane) {
;     ...
;         for (int q = 0; q < R; ++q) { ok[q] = r0 + q * NGW < nrows; rr[q] = ok[q] ? r0 + q * NGW : r0; }
;         float v[R][32]; float s1[R], s2[R];
; #pragma unroll
;         for (int q = 0; q < R; ++q) {
;             const u32x4* yb = (const u32x4*)(hb + (size_t)rr[q] * D) + lane;
;             u32x4 yv[4];
; #pragma unroll
;             for (int j = 0; j < 4; ++j) yv[j] = __builtin_nontemporal_load(yb + 64 * j);
;             if (layer == 0) {
;                 const f32x4* src32 = (const f32x4*)(rr[q] < SEQ ? p.x + (size_t)rr[q] * D : p.meta + (size_t)(rr[q] - SEQ) * D) + 2 * lane;
; #pragma unroll
;                 for (int j = 0; j < 4; ++j) { const f32x4 a0 = src32[128 * j], a1 = src32[128 * j + 1];
;                     v[q][8 * j + 0] = a0[0]; v[q][8 * j + 1] = a0[1]; v[q][8 * j + 2] = a0[2]; v[q][8 * j + 3] = a0[3];
;                     v[q][8 * j + 4] = a1[0]; v[q][8 * j + 5] = a1[1]; v[q][8 * j + 6] = a1[2]; v[q][8 * j + 7] = a1[3]; }
;             } else {
;                 const u32x4* src16 = (const u32x4*)(h16in + (size_t)rr[q] * D) + lane;
; #pragma unroll
;                 for (int j = 0; j < 4; ++j) { const u32x4 hh = __builtin_nontemporal_load(src16 + 64 * j);
;                     v[q][8 * j + 0] = h_lo(hh.x); v[q][8 * j + 1] = h_hi(hh.x); v[q][8 * j + 2] = h_lo(hh.y); v[q][8 * j + 3] = h_hi(hh.y);
;                     v[q][8 * j + 4] = h_lo(hh.z); v[q][8 * j + 5] = h_hi(hh.z); v[q][8 * j + 6] = h_lo(hh.w); v[q][8 * j + 7] = h_hi(hh.w); }
;             }
.LBB0_360:
	s_add_i32 s11, s9, s10
	s_cmp_lt_i32 s11, s8
	s_cselect_b64 s[4:5], -1, 0
	s_and_b64 s[6:7], s[4:5], exec
	s_cselect_b32 s56, s11, s10
	s_ashr_i32 s57, s56, 31
	s_lshl_b64 s[58:59], s[56:57], 12
	v_lshl_add_u64 v[134:135], v[100:101], 0, s[58:59]
	global_load_dwordx4 v[62:65], v[134:135], off nt
	global_load_dwordx4 v[38:41], v[134:135], off offset:1024 nt
	global_load_dwordx4 v[34:37], v[134:135], off offset:2048 nt
	global_load_dwordx4 v[26:29], v[134:135], off offset:3072 nt
	s_andn2_b64 vcc, exec, s[40:41]
	s_cbranch_vccnz .LBB0_400
	v_lshl_add_u64 v[78:79], v[102:103], 0, s[58:59]
	global_load_dwordx4 v[66:69], v[78:79], off nt
	global_load_dwordx4 v[70:73], v[78:79], off offset:1024 nt
	global_load_dwordx4 v[74:77], v[78:79], off offset:2048 nt
	global_load_dwordx4 v[136:139], v[78:79], off offset:3072 nt
	s_waitcnt vmcnt(11)
	v_cvt_f32_f16_e32 v50, v14
	v_cvt_f32_f16_sdwa v51, v14 dst_sel:DWORD dst_unused:UNUSED_PAD src0_sel:WORD_1
	v_cvt_f32_f16_e32 v52, v15
	v_cvt_f32_f16_sdwa v53, v15 dst_sel:DWORD dst_unused:UNUSED_PAD src0_sel:WORD_1
	v_cvt_f32_f16_e32 v42, v16
	v_cvt_f32_f16_sdwa v43, v16 dst_sel:DWORD dst_unused:UNUSED_PAD src0_sel:WORD_1
	v_cvt_f32_f16_e32 v44, v17
	v_cvt_f32_f16_sdwa v45, v17 dst_sel:DWORD dst_unused:UNUSED_PAD src0_sel:WORD_1
	s_waitcnt vmcnt(10)
	v_cvt_f32_f16_e32 v54, v18
	v_cvt_f32_f16_sdwa v55, v18 dst_sel:DWORD dst_unused:UNUSED_PAD src0_sel:WORD_1
	v_cvt_f32_f16_e32 v56, v19
	v_cvt_f32_f16_sdwa v57, v19 dst_sel:DWORD dst_unused:UNUSED_PAD src0_sel:WORD_1
	v_cvt_f32_f16_e32 v46, v20
	v_cvt_f32_f16_sdwa v47, v20 dst_sel:DWORD dst_unused:UNUSED_PAD src0_sel:WORD_1
	v_cvt_f32_f16_e32 v48, v21
	v_cvt_f32_f16_sdwa v49, v21 dst_sel:DWORD dst_unused:UNUSED_PAD src0_sel:WORD_1
	s_waitcnt vmcnt(9)
	v_cvt_f32_f16_e32 v58, v22
	v_cvt_f32_f16_sdwa v59, v22 dst_sel:DWORD dst_unused:UNUSED_PAD src0_sel:WORD_1
	v_cvt_f32_f16_e32 v60, v23
	v_cvt_f32_f16_sdwa v61, v23 dst_sel:DWORD dst_unused:UNUSED_PAD src0_sel:WORD_1
	v_cvt_f32_f16_e32 v22, v24
	v_cvt_f32_f16_sdwa v23, v24 dst_sel:DWORD dst_unused:UNUSED_PAD src0_sel:WORD_1
	v_cvt_f32_f16_e32 v24, v25
	v_cvt_f32_f16_sdwa v25, v25 dst_sel:DWORD dst_unused:UNUSED_PAD src0_sel:WORD_1
	s_waitcnt vmcnt(8)
	v_cvt_f32_f16_e32 v14, v228
	v_cvt_f32_f16_sdwa v15, v228 dst_sel:DWORD dst_unused:UNUSED_PAD src0_sel:WORD_1
	v_cvt_f32_f16_e32 v16, v229
	v_cvt_f32_f16_sdwa v17, v229 dst_sel:DWORD dst_unused:UNUSED_PAD src0_sel:WORD_1
	v_cvt_f32_f16_e32 v18, v230
	v_cvt_f32_f16_sdwa v19, v230 dst_sel:DWORD dst_unused:UNUSED_PAD src0_sel:WORD_1
	v_cvt_f32_f16_e32 v20, v231
	v_cvt_f32_f16_sdwa v21, v231 dst_sel:DWORD dst_unused:UNUSED_PAD src0_sel:WORD_1
	s_waitcnt vmcnt(3)
	v_cvt_f32_f16_e32 v94, v66
	v_cvt_f32_f16_sdwa v95, v66 dst_sel:DWORD dst_unused:UNUSED_PAD src0_sel:WORD_1
	v_cvt_f32_f16_e32 v96, v67
	v_cvt_f32_f16_sdwa v97, v67 dst_sel:DWORD dst_unused:UNUSED_PAD src0_sel:WORD_1
	v_cvt_f32_f16_e32 v82, v68
	v_cvt_f32_f16_sdwa v83, v68 dst_sel:DWORD dst_unused:UNUSED_PAD src0_sel:WORD_1
	v_cvt_f32_f16_e32 v84, v69
	v_cvt_f32_f16_sdwa v85, v69 dst_sel:DWORD dst_unused:UNUSED_PAD src0_sel:WORD_1
	s_waitcnt vmcnt(2)
	v_cvt_f32_f16_e32 v90, v70
	v_cvt_f32_f16_sdwa v91, v70 dst_sel:DWORD dst_unused:UNUSED_PAD src0_sel:WORD_1
	v_cvt_f32_f16_e32 v92, v71
	v_cvt_f32_f16_sdwa v93, v71 dst_sel:DWORD dst_unused:UNUSED_PAD src0_sel:WORD_1
	v_cvt_f32_f16_e32 v70, v72
	v_cvt_f32_f16_sdwa v71, v72 dst_sel:DWORD dst_unused:UNUSED_PAD src0_sel:WORD_1
	v_cvt_f32_f16_e32 v72, v73
	v_cvt_f32_f16_sdwa v73, v73 dst_sel:DWORD dst_unused:UNUSED_PAD src0_sel:WORD_1
	s_waitcnt vmcnt(1)
	v_cvt_f32_f16_e32 v86, v74
	v_cvt_f32_f16_sdwa v87, v74 dst_sel:DWORD dst_unused:UNUSED_PAD src0_sel:WORD_1
	v_cvt_f32_f16_e32 v88, v75
	v_cvt_f32_f16_sdwa v89, v75 dst_sel:DWORD dst_unused:UNUSED_PAD src0_sel:WORD_1
	v_cvt_f32_f16_e32 v78, v76
	v_cvt_f32_f16_sdwa v79, v76 dst_sel:DWORD dst_unused:UNUSED_PAD src0_sel:WORD_1
	v_cvt_f32_f16_e32 v80, v77
	v_cvt_f32_f16_sdwa v81, v77 dst_sel:DWORD dst_unused:UNUSED_PAD src0_sel:WORD_1
	s_waitcnt vmcnt(0)
	v_cvt_f32_f16_e32 v74, v136
	v_cvt_f32_f16_sdwa v75, v136 dst_sel:DWORD dst_unused:UNUSED_PAD src0_sel:WORD_1
	v_cvt_f32_f16_e32 v76, v137
	v_cvt_f32_f16_sdwa v77, v137 dst_sel:DWORD dst_unused:UNUSED_PAD src0_sel:WORD_1
	v_cvt_f32_f16_e32 v66, v138
	v_cvt_f32_f16_sdwa v67, v138 dst_sel:DWORD dst_unused:UNUSED_PAD src0_sel:WORD_1
	v_cvt_f32_f16_e32 v68, v139
	v_cvt_f32_f16_sdwa v69, v139 dst_sel:DWORD dst_unused:UNUSED_PAD src0_sel:WORD_1
	s_cbranch_execnz .LBB0_363
